# S5 chunk loop: running pointers instead of per-chunk address recomputation, dropped no-op adds (fewer instructions in an issue-bound loop)
# baseline (speedup 1.0000x reference)
.LBB0_302:
	s_or_b64 exec, exec, s[54:55]
	v_cndmask_b32_e64 v0, v151, v119, s[4:5]
	v_mov_b32_e32 v126, 0xffffa000
	v_lshlrev_b32_e32 v119, 8, v151
	v_lshl_add_u32 v0, v0, 10, v126
	v_cndmask_b32_e64 v0, v119, v0, s[4:5]
	v_or_b32_e32 v128, v0, v133
	v_ashrrev_i32_e32 v129, 31, v128
	v_lshlrev_b32_e32 v139, 4, v121
	v_lshlrev_b64 v[126:127], 12, v[128:129]
	v_lshl_add_u64 v[126:127], s[12:13], 0, v[126:127]
	v_lshlrev_b32_e32 v0, 2, v139
	v_lshl_add_u64 v[130:131], v[126:127], 0, v[0:1]
	v_mov_b32_e32 v119, v1
	v_lshl_add_u64 v[126:127], v[130:131], 0, v[118:119]
	v_mov_b32_e32 v0, 0xc648000
	v_mov_b32_e32 v119, 0x9e48000
	v_cndmask_b32_e32 v0, v0, v119, vcc
	v_lshl_add_u64 v[166:167], s[28:29], 0, v[0:1]
	v_lshlrev_b64 v[128:129], 11, v[128:129]
	v_lshl_add_u64 v[128:129], v[166:167], 0, v[128:129]
	s_waitcnt vmcnt(25)
	v_pk_mul_f32 v[166:167], v[142:143], v[98:99] op_sel:[1,0]
	v_pk_mul_f32 v[98:99], v[142:143], v[98:99] op_sel_hi:[0,1]
	v_pk_fma_f32 v[166:167], v[142:143], v[94:95], v[166:167] op_sel_hi:[0,1,1] neg_lo:[0,0,1] neg_hi:[0,0,1]
	v_pk_fma_f32 v[94:95], v[142:143], v[94:95], v[98:99] op_sel:[1,0,0]
	v_pk_mul_f32 v[98:99], v[142:143], v[100:101] op_sel:[1,0]
	v_pk_mul_f32 v[100:101], v[142:143], v[100:101] op_sel_hi:[0,1]
	v_pk_fma_f32 v[98:99], v[142:143], v[96:97], v[98:99] op_sel_hi:[0,1,1] neg_lo:[0,0,1] neg_hi:[0,0,1]
	v_pk_fma_f32 v[96:97], v[142:143], v[96:97], v[100:101] op_sel:[1,0,0]
	v_pk_mul_f32 v[100:101], v[142:143], v[10:11] op_sel:[1,0]
	v_pk_mul_f32 v[10:11], v[142:143], v[10:11] op_sel_hi:[0,1]
	v_pk_fma_f32 v[168:169], v[142:143], v[6:7], v[10:11] op_sel:[1,0,0]
	v_cvt_pk_bf16_f32 v10, v94, v95
	s_waitcnt vmcnt(20)
	v_pk_mul_f32 v[94:95], v[140:141], v[90:91] op_sel:[1,0]
	v_pk_mul_f32 v[90:91], v[140:141], v[90:91] op_sel_hi:[0,1]
	v_pk_fma_f32 v[94:95], v[140:141], v[86:87], v[94:95] op_sel_hi:[0,1,1] neg_lo:[0,0,1] neg_hi:[0,0,1]
	v_pk_fma_f32 v[86:87], v[140:141], v[86:87], v[90:91] op_sel:[1,0,0]
	v_pk_mul_f32 v[90:91], v[140:141], v[92:93] op_sel:[1,0]
	v_pk_mul_f32 v[92:93], v[140:141], v[92:93] op_sel_hi:[0,1]
	v_pk_fma_f32 v[90:91], v[140:141], v[88:89], v[90:91] op_sel_hi:[0,1,1] neg_lo:[0,0,1] neg_hi:[0,0,1]
	v_pk_fma_f32 v[88:89], v[140:141], v[88:89], v[92:93] op_sel:[1,0,0]
	v_pk_mul_f32 v[92:93], v[140:141], v[18:19] op_sel:[1,0]
	v_pk_mul_f32 v[18:19], v[140:141], v[18:19] op_sel_hi:[0,1]
	v_lshlrev_b32_e32 v0, 1, v139
	v_cvt_pk_bf16_f32 v11, v96, v97
	v_pk_fma_f32 v[96:97], v[140:141], v[14:15], v[18:19] op_sel:[1,0,0]
	v_cvt_pk_bf16_f32 v18, v86, v87
	s_waitcnt vmcnt(15)
	v_pk_mul_f32 v[86:87], v[136:137], v[82:83] op_sel:[1,0]
	v_pk_mul_f32 v[82:83], v[136:137], v[82:83] op_sel_hi:[0,1]
	v_lshl_add_u64 v[128:129], v[128:129], 0, v[0:1]
	v_lshlrev_b32_e32 v0, 1, v106
	v_pk_fma_f32 v[86:87], v[136:137], v[78:79], v[86:87] op_sel_hi:[0,1,1] neg_lo:[0,0,1] neg_hi:[0,0,1]
	v_pk_fma_f32 v[78:79], v[136:137], v[78:79], v[82:83] op_sel:[1,0,0]
	v_pk_mul_f32 v[82:83], v[136:137], v[84:85] op_sel:[1,0]
	v_pk_mul_f32 v[84:85], v[136:137], v[84:85] op_sel_hi:[0,1]
	v_lshl_add_u64 v[128:129], v[128:129], 0, v[0:1]
	v_lshlrev_b32_e32 v0, 2, v106
	v_pk_fma_f32 v[82:83], v[136:137], v[80:81], v[82:83] op_sel_hi:[0,1,1] neg_lo:[0,0,1] neg_hi:[0,0,1]
	v_pk_fma_f32 v[80:81], v[136:137], v[80:81], v[84:85] op_sel:[1,0,0]
	v_pk_mul_f32 v[84:85], v[136:137], v[26:27] op_sel:[1,0]
	v_pk_mul_f32 v[26:27], v[136:137], v[26:27] op_sel_hi:[0,1]
	v_lshl_add_u64 v[130:131], v[130:131], 0, v[0:1]
	v_pk_fma_f32 v[100:101], v[142:143], v[6:7], v[100:101] op_sel_hi:[0,1,1] neg_lo:[0,0,1] neg_hi:[0,0,1]
	v_pk_mul_f32 v[6:7], v[142:143], v[12:13] op_sel:[1,0]
	v_cvt_pk_bf16_f32 v19, v88, v89
	v_pk_fma_f32 v[88:89], v[136:137], v[22:23], v[26:27] op_sel:[1,0,0]
	v_cvt_pk_bf16_f32 v26, v78, v79
	s_waitcnt vmcnt(10)
	v_pk_mul_f32 v[78:79], v[134:135], v[74:75] op_sel:[1,0]
	v_pk_mul_f32 v[74:75], v[134:135], v[74:75] op_sel_hi:[0,1]
	s_waitcnt vmcnt(7)
	v_xor_b32_e32 v0, 0x80000000, v66
	v_pk_fma_f32 v[170:171], v[142:143], v[8:9], v[6:7] op_sel_hi:[0,1,1] neg_lo:[0,0,1] neg_hi:[0,0,1]
	v_pk_mul_f32 v[6:7], v[142:143], v[12:13] op_sel_hi:[0,1]
	v_pk_fma_f32 v[92:93], v[140:141], v[14:15], v[92:93] op_sel_hi:[0,1,1] neg_lo:[0,0,1] neg_hi:[0,0,1]
	v_pk_mul_f32 v[14:15], v[140:141], v[20:21] op_sel:[1,0]
	v_pk_fma_f32 v[78:79], v[134:135], v[70:71], v[78:79] op_sel_hi:[0,1,1] neg_lo:[0,0,1] neg_hi:[0,0,1]
	v_pk_fma_f32 v[70:71], v[134:135], v[70:71], v[74:75] op_sel:[1,0,0]
	v_pk_mul_f32 v[74:75], v[134:135], v[76:77] op_sel:[1,0]
	v_pk_mul_f32 v[76:77], v[134:135], v[76:77] op_sel_hi:[0,1]
	v_cvt_pk_bf16_f32 v38, v38, v0
	s_waitcnt vmcnt(6)
	v_xor_b32_e32 v0, 0x80000000, v62
	v_pk_fma_f32 v[142:143], v[142:143], v[8:9], v[6:7] op_sel:[1,0,0]
	v_cvt_pk_bf16_f32 v7, v98, v99
	v_pk_fma_f32 v[98:99], v[140:141], v[16:17], v[14:15] op_sel_hi:[0,1,1] neg_lo:[0,0,1] neg_hi:[0,0,1]
	v_pk_mul_f32 v[14:15], v[140:141], v[20:21] op_sel_hi:[0,1]
	v_pk_fma_f32 v[84:85], v[136:137], v[22:23], v[84:85] op_sel_hi:[0,1,1] neg_lo:[0,0,1] neg_hi:[0,0,1]
	v_pk_mul_f32 v[22:23], v[136:137], v[28:29] op_sel:[1,0]
	v_pk_fma_f32 v[74:75], v[134:135], v[72:73], v[74:75] op_sel_hi:[0,1,1] neg_lo:[0,0,1] neg_hi:[0,0,1]
	v_pk_fma_f32 v[72:73], v[134:135], v[72:73], v[76:77] op_sel:[1,0,0]
	v_pk_mul_f32 v[76:77], v[134:135], v[34:35] op_sel:[1,0]
	v_pk_mul_f32 v[34:35], v[134:135], v[34:35] op_sel_hi:[0,1]
	v_cvt_pk_bf16_f32 v42, v42, v0
	s_waitcnt vmcnt(3)
	v_xor_b32_e32 v0, 0x80000000, v58
	v_cvt_pk_bf16_f32 v8, v100, v101
	v_pk_fma_f32 v[100:101], v[140:141], v[16:17], v[14:15] op_sel:[1,0,0]
	v_cvt_pk_bf16_f32 v15, v90, v91
	v_pk_fma_f32 v[90:91], v[136:137], v[24:25], v[22:23] op_sel_hi:[0,1,1] neg_lo:[0,0,1] neg_hi:[0,0,1]
	v_pk_mul_f32 v[22:23], v[136:137], v[28:29] op_sel_hi:[0,1]
	v_cvt_pk_bf16_f32 v27, v80, v81
	v_pk_fma_f32 v[76:77], v[134:135], v[30:31], v[76:77] op_sel_hi:[0,1,1] neg_lo:[0,0,1] neg_hi:[0,0,1]
	v_pk_fma_f32 v[80:81], v[134:135], v[30:31], v[34:35] op_sel:[1,0,0]
	v_pk_mul_f32 v[30:31], v[134:135], v[36:37] op_sel:[1,0]
	v_cvt_pk_bf16_f32 v46, v46, v0
	s_waitcnt vmcnt(2)
	v_xor_b32_e32 v0, 0x80000000, v54
	v_xor_b32_e32 v54, 0x80000000, v55
	v_mov_b32_e32 v139, v1
	v_cvt_pk_bf16_f32 v16, v92, v93
	v_pk_fma_f32 v[92:93], v[136:137], v[24:25], v[22:23] op_sel:[1,0,0]
	v_cvt_pk_bf16_f32 v23, v82, v83
	v_pk_fma_f32 v[82:83], v[134:135], v[32:33], v[30:31] op_sel_hi:[0,1,1] neg_lo:[0,0,1] neg_hi:[0,0,1]
	v_pk_mul_f32 v[30:31], v[134:135], v[36:37] op_sel_hi:[0,1]
	v_cvt_pk_bf16_f32 v51, v51, v54
	v_lshlrev_b64 v[54:55], 12, v[138:139]
	v_cvt_pk_bf16_f32 v24, v84, v85
	v_pk_fma_f32 v[84:85], v[134:135], v[32:33], v[30:31] op_sel:[1,0,0]
	v_lshl_add_u64 v[54:55], v[126:127], 0, v[54:55]
	v_cvt_pk_bf16_f32 v22, v86, v87
	v_cvt_pk_bf16_f32 v28, v88, v89
	v_cvt_pk_bf16_f32 v33, v82, v83
	v_cvt_pk_bf16_f32 v37, v84, v85
	global_load_dwordx4 v[82:85], v[54:55], off offset:16
	global_load_dwordx4 v[86:89], v[54:55], off
	v_add_u32_e32 v54, v165, v138
	v_ashrrev_i32_e32 v55, 31, v54
	v_cvt_pk_bf16_f32 v34, v70, v71
	v_xor_b32_e32 v70, 0x80000000, v56
	v_xor_b32_e32 v71, 0x80000000, v57
	v_lshlrev_b64 v[56:57], 12, v[54:55]
	v_add_u32_e32 v54, v54, v165
	v_ashrrev_i32_e32 v55, 31, v54
	v_xor_b32_e32 v66, 0x80000000, v67
	v_xor_b32_e32 v67, 0x80000000, v68
	v_xor_b32_e32 v58, 0x80000000, v59
	v_xor_b32_e32 v59, 0x80000000, v60
	v_lshlrev_b64 v[54:55], 12, v[54:55]
	v_xor_b32_e32 v68, 0x80000000, v69
	v_cvt_pk_bf16_f32 v39, v39, v66
	v_cvt_pk_bf16_f32 v40, v40, v67
	v_xor_b32_e32 v62, 0x80000000, v63
	v_xor_b32_e32 v63, 0x80000000, v64
	v_xor_b32_e32 v64, 0x80000000, v65
	v_xor_b32_e32 v60, 0x80000000, v61
	v_cvt_pk_bf16_f32 v47, v47, v58
	v_cvt_pk_bf16_f32 v48, v48, v59
	v_lshl_add_u64 v[66:67], v[126:127], 0, v[56:57]
	v_lshl_add_u64 v[58:59], v[126:127], 0, v[54:55]
	v_cvt_pk_bf16_f32 v41, v41, v68
	v_cvt_pk_bf16_f32 v43, v43, v62
	v_cvt_pk_bf16_f32 v44, v44, v63
	v_cvt_pk_bf16_f32 v45, v45, v64
	v_cvt_pk_bf16_f32 v49, v49, v60
	global_load_dwordx4 v[54:57], v[58:59], off offset:16
	s_nop 0
	global_load_dwordx4 v[58:61], v[58:59], off
	s_nop 0
	global_load_dwordx4 v[62:65], v[66:67], off offset:16
	s_nop 0
	global_load_dwordx4 v[66:69], v[66:67], off
	v_cvt_pk_bf16_f32 v52, v52, v70
	v_mul_u32_u24_e32 v70, 0x84, v125
	v_cvt_pk_bf16_f32 v17, v98, v99
	v_lshl_add_u32 v98, v70, 2, v147
	v_mul_u32_u24_e32 v70, 0x84, v154
	v_lshl_add_u32 v99, v70, 2, v147
	v_mul_u32_u24_e32 v70, 0x84, v155
	v_cvt_pk_bf16_f32 v21, v100, v101
	v_lshl_add_u32 v100, v70, 2, v147
	v_mul_u32_u24_e32 v70, 0x84, v157
	v_lshl_add_u32 v101, v70, 2, v147
	v_mul_u32_u24_e32 v70, 0x84, v152
	v_lshl_add_u32 v119, v70, 2, v147
	v_mul_u32_u24_e32 v70, 0x84, v159
	v_lshl_add_u32 v134, v70, 2, v147
	v_mul_u32_u24_e32 v70, 0x84, v153
	v_lshl_add_u32 v135, v70, 2, v147
	v_add_u32_e32 v70, 7, v150
	v_cvt_pk_bf16_f32 v53, v53, v71
	v_mul_u32_u24_e32 v71, 0x84, v70
	v_lshl_add_u32 v136, v71, 2, v147
	v_sub_u32_e32 v71, 8, v150
	v_cvt_pk_bf16_f32 v35, v72, v73
	v_mul_u32_u24_e32 v72, 0x84, v71
	v_lshl_add_u32 v137, v72, 2, v147
	v_mul_u32_u24_e32 v72, 0x84, v156
	v_lshl_add_u32 v138, v72, 2, v147
	v_mul_u32_u24_e32 v72, 0x84, v158
	v_lshl_add_u32 v139, v72, 2, v147
	v_mul_u32_u24_e32 v72, 0x84, v160
	v_lshl_add_u32 v140, v72, 2, v147
	v_mul_u32_u24_e32 v72, 0x84, v161
	v_lshl_add_u32 v141, v72, 2, v147
	v_mul_u32_u24_e32 v72, 0x84, v162
	v_cvt_pk_bf16_f32 v13, v142, v143
	v_lshl_add_u32 v142, v72, 2, v147
	v_mul_u32_u24_e32 v72, 0x84, v163
	v_lshl_add_u32 v143, v72, 2, v147
	v_mul_u32_u24_e32 v72, 0x84, v164
	v_cvt_pk_bf16_f32 v31, v74, v75
	v_cvt_pk_bf16_f32 v32, v76, v77
	v_cvt_pk_bf16_f32 v50, v50, v0
	v_mul_i32_i24_e32 v0, 3, v165
	v_lshl_add_u32 v165, v72, 2, v147
	v_mul_u32_u24_e32 v72, 0x110, v125
	v_mul_u32_u24_e32 v73, 0x110, v154
	v_mul_u32_u24_e32 v74, 0x110, v155
	v_mul_u32_u24_e32 v75, 0x110, v157
	v_mul_u32_u24_e32 v76, 0x110, v152
	v_mul_u32_u24_e32 v77, 0x110, v159
	v_mul_u32_u24_e32 v70, 0x110, v70
	v_mul_u32_u24_e32 v71, 0x110, v71
	v_cvt_pk_bf16_f32 v12, v168, v169
	v_cvt_pk_bf16_f32 v20, v96, v97
	v_cvt_pk_bf16_f32 v30, v78, v79
	v_cvt_pk_bf16_f32 v36, v80, v81
	v_mul_u32_u24_e32 v78, 0x110, v153
	v_mul_u32_u24_e32 v79, 0x110, v156
	v_mul_u32_u24_e32 v80, 0x110, v158
	v_mul_u32_u24_e32 v81, 0x110, v160
	v_mul_u32_u24_e32 v96, 0x110, v161
	v_mul_u32_u24_e32 v97, 0x110, v162
	v_mul_u32_u24_e32 v125, 0x110, v163
	v_mul_u32_u24_e32 v168, 0x110, v164
	v_add_u32_e32 v152, v147, v72
	v_add_u32_e32 v153, v147, v73
	v_add_u32_e32 v154, v147, v74
	v_add_u32_e32 v155, v147, v75
	v_add_u32_e32 v156, v147, v76
	v_add_u32_e32 v157, v147, v77
	v_add_u32_e32 v159, v147, v70
	v_add_u32_e32 v160, v147, v71
	s_mov_b32 s22, 0
	v_cvt_pk_bf16_f32 v6, v166, v167
	v_cvt_pk_bf16_f32 v9, v170, v171
	v_cvt_pk_bf16_f32 v14, v94, v95
	s_waitcnt vmcnt(3)
	v_mov_b64_e32 v[72:73], v[56:57]
	s_waitcnt vmcnt(2)
	v_mov_b64_e32 v[76:77], v[60:61]
	v_cvt_pk_bf16_f32 v25, v90, v91
	v_cvt_pk_bf16_f32 v29, v92, v93
	v_mov_b32_e32 v90, 0
	v_cndmask_b32_e32 v90, v146, v90, vcc
	v_mov_b32_e32 v91, 0
	v_lshlrev_b64 v[90:91], 11, v[90:91]
	s_cmp_lg_u64 vcc, 0
	s_mov_b32 s98, 0x8000
	s_mov_b32 s99, 0
	s_cbranch_scc1 .Ls5_step_done
	s_mov_b32 s98, 0xffff8000
	s_mov_b32 s99, -1
.Ls5_step_done:
	v_lshl_add_u64 v[128:129], v[90:91], 0, v[128:129]
	v_lshl_add_u64 v[130:131], v[90:91], 1, v[130:131]
	v_lshl_add_u64 v[126:127], v[90:91], 1, v[126:127]
	global_load_dwordx4 v[90:93], v[130:131], off
	v_lshl_add_u64 v[130:131], s[98:99], 1, v[130:131]
	v_lshl_add_u64 v[126:127], s[98:99], 2, v[126:127]
	v_lshl_add_u64 v[126:127], s[98:99], 1, v[126:127]


	s_mov_b64 s[54:55], 0
	v_add_u32_e32 v158, v147, v78
	v_add_u32_e32 v161, v147, v79
	v_add_u32_e32 v162, v147, v80
	v_add_u32_e32 v163, v147, v81
	v_add_u32_e32 v164, v147, v96
	v_add_u32_e32 v166, v147, v97
	v_add_u32_e32 v167, v147, v125
	v_add_u32_e32 v168, v147, v168
	v_mov_b32_e32 v169, v146
	s_mov_b32 s23, 0
	v_mov_b64_e32 v[70:71], v[54:55]
	v_mov_b64_e32 v[74:75], v[58:59]
	s_waitcnt vmcnt(0)
	v_cvt_pk_bf16_f32 v125, v86, v87
	v_lshlrev_b32_e32 v170, 16, v125
	v_and_b32_e32 v171, 0xffff0000, v125
	v_cvt_pk_bf16_f32 v172, v88, v89
	v_pk_add_f32 v[86:87], v[86:87], v[170:171] neg_lo:[0,1] neg_hi:[0,1]
	v_cvt_pk_bf16_f32 v173, v82, v83
	v_cvt_pk_bf16_f32 v170, v86, v87
	v_lshlrev_b32_e32 v86, 16, v172
	v_and_b32_e32 v87, 0xffff0000, v172
	v_pk_add_f32 v[86:87], v[88:89], v[86:87] neg_lo:[0,1] neg_hi:[0,1]
	v_cvt_pk_bf16_f32 v178, v84, v85
	v_cvt_pk_bf16_f32 v88, v86, v87
	v_lshlrev_b32_e32 v86, 16, v173
	v_and_b32_e32 v87, 0xffff0000, v173
	v_pk_add_f32 v[82:83], v[82:83], v[86:87] neg_lo:[0,1] neg_hi:[0,1]
	v_cvt_pk_bf16_f32 v86, v82, v83
	v_lshlrev_b32_e32 v82, 16, v178
	v_and_b32_e32 v83, 0xffff0000, v178
	v_pk_add_f32 v[82:83], v[84:85], v[82:83] neg_lo:[0,1] neg_hi:[0,1]
	v_cndmask_b32_e64 v84, v86, v173, s[6:7]
	v_cvt_pk_bf16_f32 v82, v82, v83
	v_cndmask_b32_e64 v85, v82, v178, s[6:7]
	v_cndmask_b32_e64 v83, v88, v172, s[6:7]
	v_cndmask_b32_e64 v82, v170, v125, s[6:7]
	s_nop 1
	v_mfma_f32_16x16x32_bf16 v[86:89], v[6:9], v[82:85], 0
	v_mfma_f32_16x16x32_bf16 v[170:173], v[14:17], v[82:85], 0
	v_mfma_f32_16x16x32_bf16 v[178:181], v[22:25], v[82:85], 0
	v_mfma_f32_16x16x32_bf16 v[182:185], v[30:33], v[82:85], 0
	v_mfma_f32_16x16x32_bf16 v[186:189], v[10:13], v[82:85], 0
	v_mfma_f32_16x16x32_bf16 v[210:213], v[18:21], v[82:85], 0
	v_mfma_f32_16x16x32_bf16 v[214:217], v[26:29], v[82:85], 0
	v_mfma_f32_16x16x32_bf16 v[82:85], v[34:37], v[82:85], 0
	s_nop 0
	ds_write_b128 v148, v[86:89]
	ds_write_b128 v148, v[170:173] offset:64
	ds_write_b128 v148, v[178:181] offset:128
	ds_write_b128 v148, v[182:185] offset:192
	ds_write_b128 v148, v[186:189] offset:256
	ds_write_b128 v148, v[210:213] offset:320
	ds_write_b128 v148, v[214:217] offset:384
	ds_write_b128 v148, v[82:85] offset:448
	s_branch .LBB0_304
.LBB0_303:
	ds_read2st64_b32 v[82:83], v98 offset1:1
	ds_read2st64_b32 v[84:85], v99 offset1:1
	ds_read2st64_b32 v[86:87], v100 offset1:1
	ds_read2st64_b32 v[88:89], v101 offset1:1
	ds_read2st64_b32 v[170:171], v119 offset1:1
	ds_read2st64_b32 v[172:173], v134 offset1:1
	ds_read2st64_b32 v[178:179], v135 offset1:1
	ds_read2st64_b32 v[180:181], v136 offset1:1
	ds_read2st64_b32 v[182:183], v137 offset1:1
	ds_read2st64_b32 v[184:185], v138 offset1:1
	ds_read2st64_b32 v[186:187], v139 offset1:1
	ds_read2st64_b32 v[188:189], v140 offset1:1
	ds_read2st64_b32 v[190:191], v141 offset1:1
	ds_read2st64_b32 v[202:203], v142 offset1:1
	ds_read2st64_b32 v[204:205], v143 offset1:1
	ds_read2st64_b32 v[210:211], v165 offset1:1
	v_cvt_pk_bf16_f32 v222, v66, v67
	v_cvt_pk_bf16_f32 v223, v68, v69
	v_cvt_pk_bf16_f32 v224, v62, v63
	v_cvt_pk_bf16_f32 v225, v64, v65
	v_lshlrev_b32_e32 v226, 16, v222
	v_and_b32_e32 v227, 0xffff0000, v222
	v_pk_add_f32 v[228:229], v[66:67], v[226:227] neg_lo:[0,1] neg_hi:[0,1]
	v_cvt_pk_bf16_f32 v230, v228, v229
	v_lshlrev_b32_e32 v226, 16, v223
	v_and_b32_e32 v227, 0xffff0000, v223
	v_pk_add_f32 v[228:229], v[68:69], v[226:227] neg_lo:[0,1] neg_hi:[0,1]
	v_cvt_pk_bf16_f32 v231, v228, v229
	v_lshlrev_b32_e32 v226, 16, v224
	v_and_b32_e32 v227, 0xffff0000, v224
	v_pk_add_f32 v[228:229], v[62:63], v[226:227] neg_lo:[0,1] neg_hi:[0,1]
	v_cvt_pk_bf16_f32 v232, v228, v229
	v_lshlrev_b32_e32 v226, 16, v225
	v_and_b32_e32 v227, 0xffff0000, v225
	v_pk_add_f32 v[228:229], v[64:65], v[226:227] neg_lo:[0,1] neg_hi:[0,1]
	v_cvt_pk_bf16_f32 v233, v228, v229
	v_cndmask_b32_e64 v218, v230, v222, s[6:7]
	v_cndmask_b32_e64 v219, v231, v223, s[6:7]
	v_cndmask_b32_e64 v220, v232, v224, s[6:7]
	v_cndmask_b32_e64 v221, v233, v225, s[6:7]
	s_add_i32 s23, s23, 1
	v_cmp_eq_u32_e64 s[0:1], s23, v145
	s_waitcnt lgkmcnt(8)
	v_mfma_f32_16x16x32_bf16 v[222:225], v[6:9], v[218:221], 0
	v_fma_f32 v250, -v123, v132, v82
	v_fma_f32 v209, v123, v124, v83
	v_fma_f32 v216, v122, v124, v250
	v_fma_f32 v217, v122, v132, v209
	v_cvt_pk_bf16_f32 v250, v216, v217
	ds_write_b32 v152, v250 offset:8448
	v_mfma_f32_16x16x32_bf16 v[226:229], v[14:17], v[218:221], 0
	v_fma_f32 v250, -v123, v217, v84
	v_fma_f32 v209, v123, v216, v85
	v_fma_f32 v124, v122, v216, v250
	v_fma_f32 v132, v122, v217, v209
	v_cvt_pk_bf16_f32 v250, v124, v132
	ds_write_b32 v153, v250 offset:8448
	v_mfma_f32_16x16x32_bf16 v[230:233], v[22:25], v[218:221], 0
	v_fma_f32 v250, -v123, v132, v86
	v_fma_f32 v209, v123, v124, v87
	v_fma_f32 v216, v122, v124, v250
	v_fma_f32 v217, v122, v132, v209
	v_cvt_pk_bf16_f32 v250, v216, v217
	ds_write_b32 v154, v250 offset:8448
	v_mfma_f32_16x16x32_bf16 v[234:237], v[30:33], v[218:221], 0
	v_fma_f32 v250, -v123, v217, v88
	v_fma_f32 v209, v123, v216, v89
	v_fma_f32 v124, v122, v216, v250
	v_fma_f32 v132, v122, v217, v209
	v_cvt_pk_bf16_f32 v250, v124, v132
	ds_write_b32 v155, v250 offset:8448
	s_or_b64 s[54:55], s[0:1], s[54:55]
	v_mfma_f32_16x16x32_bf16 v[238:241], v[10:13], v[218:221], 0
	v_fma_f32 v250, -v123, v132, v170
	v_fma_f32 v209, v123, v124, v171
	v_fma_f32 v216, v122, v124, v250
	v_fma_f32 v217, v122, v132, v209
	v_cvt_pk_bf16_f32 v250, v216, v217
	ds_write_b32 v156, v250 offset:8448
	v_mfma_f32_16x16x32_bf16 v[242:245], v[18:21], v[218:221], 0
	v_fma_f32 v250, -v123, v217, v172
	v_fma_f32 v209, v123, v216, v173
	v_fma_f32 v124, v122, v216, v250
	v_fma_f32 v132, v122, v217, v209
	v_cvt_pk_bf16_f32 v250, v124, v132
	ds_write_b32 v157, v250 offset:8448
	v_mfma_f32_16x16x32_bf16 v[246:249], v[26:29], v[218:221], 0
	v_fma_f32 v250, -v123, v132, v178
	v_fma_f32 v209, v123, v124, v179
	v_fma_f32 v216, v122, v124, v250
	v_fma_f32 v217, v122, v132, v209
	v_cvt_pk_bf16_f32 v250, v216, v217
	ds_write_b32 v158, v250 offset:8448
	v_mfma_f32_16x16x32_bf16 v[212:215], v[34:37], v[218:221], 0
	v_fma_f32 v250, -v123, v217, v180
	v_fma_f32 v209, v123, v216, v181
	v_fma_f32 v124, v122, v216, v250
	v_fma_f32 v132, v122, v217, v209
	v_cvt_pk_bf16_f32 v250, v124, v132
	ds_write_b32 v159, v250 offset:8448
	s_waitcnt lgkmcnt(8)
	v_fma_f32 v250, -v123, v132, v182
	v_fma_f32 v209, v123, v124, v183
	v_fma_f32 v216, v122, v124, v250
	v_fma_f32 v217, v122, v132, v209
	v_cvt_pk_bf16_f32 v250, v216, v217
	ds_write_b32 v160, v250 offset:8448
	ds_write_b128 v148, v[222:225]
	ds_write_b128 v148, v[226:229] offset:64
	v_fma_f32 v250, -v123, v217, v184
	v_fma_f32 v209, v123, v216, v185
	v_fma_f32 v124, v122, v216, v250
	v_fma_f32 v132, v122, v217, v209
	v_cvt_pk_bf16_f32 v250, v124, v132
	ds_write_b32 v161, v250 offset:8448
	ds_write_b128 v148, v[230:233] offset:128
	ds_write_b128 v148, v[234:237] offset:192
	v_fma_f32 v250, -v123, v132, v186
	v_fma_f32 v209, v123, v124, v187
	v_fma_f32 v216, v122, v124, v250
	v_fma_f32 v217, v122, v132, v209
	v_cvt_pk_bf16_f32 v250, v216, v217
	ds_write_b32 v162, v250 offset:8448
	ds_write_b128 v148, v[238:241] offset:256
	ds_write_b128 v148, v[242:245] offset:320
	v_fma_f32 v250, -v123, v217, v188
	v_fma_f32 v209, v123, v216, v189
	v_fma_f32 v124, v122, v216, v250
	v_fma_f32 v132, v122, v217, v209
	v_cvt_pk_bf16_f32 v250, v124, v132
	ds_write_b32 v163, v250 offset:8448
	ds_write_b128 v148, v[246:249] offset:384
	ds_write_b128 v148, v[212:215] offset:448
	v_fma_f32 v250, -v123, v132, v190
	v_fma_f32 v209, v123, v124, v191
	v_fma_f32 v216, v122, v124, v250
	v_fma_f32 v217, v122, v132, v209
	v_cvt_pk_bf16_f32 v250, v216, v217
	ds_write_b32 v164, v250 offset:8448
	v_fma_f32 v250, -v123, v217, v202
	v_fma_f32 v209, v123, v216, v203
	v_fma_f32 v124, v122, v216, v250
	v_fma_f32 v132, v122, v217, v209
	v_cvt_pk_bf16_f32 v250, v124, v132
	ds_write_b32 v166, v250 offset:8448
	v_fma_f32 v250, -v123, v132, v204
	v_fma_f32 v209, v123, v124, v205
	v_fma_f32 v216, v122, v124, v250
	v_fma_f32 v217, v122, v132, v209
	v_cvt_pk_bf16_f32 v250, v216, v217
	ds_write_b32 v167, v250 offset:8448
	v_fma_f32 v250, -v123, v217, v210
	v_fma_f32 v209, v123, v216, v211
	v_fma_f32 v124, v122, v216, v250
	v_fma_f32 v132, v122, v217, v209
	v_cvt_pk_bf16_f32 v250, v124, v132
	ds_write_b32 v168, v250 offset:8448
	s_waitcnt lgkmcnt(0)
	ds_read_b128 v[82:85], v149 offset:8448
	ds_read_b128 v[86:89], v149 offset:8512
	ds_read_b128 v[170:173], v149 offset:8576
	ds_read_b128 v[178:181], v149 offset:8640
	s_waitcnt lgkmcnt(2)
	v_mfma_f32_16x16x32_bf16 v[86:89], v[42:45], v[86:89], 0
	v_mfma_f32_16x16x32_bf16 v[82:85], v[38:41], v[82:85], 0
	s_waitcnt lgkmcnt(0)
	v_mfma_f32_16x16x32_bf16 v[86:89], v[50:53], v[178:181], v[86:89]
	v_mfma_f32_16x16x32_bf16 v[82:85], v[46:49], v[170:173], v[82:85]
	s_nop 7
	v_pk_add_f32 v[84:85], v[84:85], v[88:89]
	v_pk_add_f32 v[82:83], v[82:83], v[86:87]
	s_waitcnt vmcnt(3)
	s_bitcmp1_b32 s23, 0
	s_cbranch_scc0 .Ls5_tail_codd
	v_pk_fma_f32 v[92:93], v[4:5], v[92:93], v[84:85]
	v_pk_fma_f32 v[90:91], v[2:3], v[90:91], v[82:83]
	v_mov_b64_e32 v[62:63], v[54:55]
	v_mov_b64_e32 v[64:65], v[56:57]
	v_mov_b64_e32 v[66:67], v[58:59]
	v_mov_b64_e32 v[68:69], v[60:61]
	v_cvt_pk_bf16_f32 v90, v90, v91
	v_cvt_pk_bf16_f32 v91, v92, v93
	global_store_dwordx2 v[128:129], v[90:91], off
	s_branch .Ls5_tail_done
.Ls5_tail_codd:
	v_pk_fma_f32 v[80:81], v[4:5], v[80:81], v[84:85]
	v_pk_fma_f32 v[78:79], v[2:3], v[78:79], v[82:83]
	v_mov_b64_e32 v[62:63], v[70:71]
	v_mov_b64_e32 v[64:65], v[72:73]
	v_mov_b64_e32 v[66:67], v[74:75]
	v_mov_b64_e32 v[68:69], v[76:77]
	v_cvt_pk_bf16_f32 v78, v78, v79
	v_cvt_pk_bf16_f32 v79, v80, v81
	global_store_dwordx2 v[128:129], v[78:79], off
.Ls5_tail_done:
	v_lshl_add_u64 v[128:129], s[98:99], 0, v[128:129]
	s_andn2_b64 exec, exec, s[54:55]
	s_cbranch_execz .LBB0_306


.LBB0_304:
	s_bitcmp1_b32 s23, 0
	s_cbranch_scc1 .Ls5_top_odd
	global_load_dwordx4 v[78:81], v[130:131], off
	global_load_dwordx4 v[70:73], v[126:127], off offset:16
	global_load_dwordx4 v[74:77], v[126:127], off
	s_branch .Ls5_top_done
.Ls5_top_odd:
	global_load_dwordx4 v[90:93], v[130:131], off
	global_load_dwordx4 v[54:57], v[126:127], off offset:16
	global_load_dwordx4 v[58:61], v[126:127], off
.Ls5_top_done:
	v_lshl_add_u64 v[130:131], s[98:99], 1, v[130:131]
	v_lshl_add_u64 v[126:127], s[98:99], 1, v[126:127]
	s_branch .LBB0_303


.LBB0_306:
	s_waitcnt vmcnt(0)
	s_or_b64 exec, exec, s[54:55]
	v_mov_b32_e32 v125, v132
	s_and_saveexec_b64 s[0:1], s[2:3]
	s_cbranch_execz .LBB0_297
	v_lshlrev_b32_e32 v0, 2, v151
	v_or3_b32 v2, v0, s20, v150
	v_ashrrev_i32_e32 v3, 31, v2
	v_lshlrev_b64 v[2:3], 14, v[2:3]
	v_lshl_add_u64 v[2:3], s[26:27], 0, v[2:3]
	v_lshlrev_b32_e32 v0, 8, v121
	v_lshl_add_u64 v[2:3], v[2:3], 0, v[0:1]
	v_mov_b32_e32 v121, v1
	v_lshl_add_u64 v[2:3], v[2:3], 0, v[120:121]
	v_add_co_u32_e32 v4, vcc, 0xa800000, v2
	s_nop 1
	v_addc_co_u32_e32 v5, vcc, 0, v3, vcc
	v_add_co_u32_e32 v2, vcc, 0xaa00000, v2
	global_store_dword v[4:5], v124, off
	s_nop 0
	v_addc_co_u32_e32 v3, vcc, 0, v3, vcc
	global_store_dword v[2:3], v125, off
	s_branch .LBB0_297
